# G1 start skew grouped by the workgroup's column in the XCD round ((bx>>5)&7) instead of (bx>>3)&7; v75 otherwise
# baseline (speedup 1.0000x reference)
.LBB0_205:
	s_bfe_u32 s4, s2, 0x30005
	s_cmp_eq_u32 s4, 0
	s_cbranch_scc1 .Lskew_done_g1
